# v50 + peeled first k-iteration with relaxed vmcnt (in-proj, kv_b, FFN1)
# speedup vs baseline: 1.0031x; 1.0031x over previous
.LBB0_268:
	s_ashr_i32 s9, s8, 31
	v_cmp_lt_i64_e32 vcc, s[16:17], v[142:143]
	s_lshl_b64 s[16:17], s[8:9], 20
	s_add_u32 s16, s88, s16
	s_addc_u32 s17, s89, s17
	s_and_b64 s[18:19], vcc, exec
	s_cselect_b32 s9, s17, s23
	s_cselect_b32 s53, s16, s22
	s_ashr_i32 s7, s6, 31
	s_lshl_b64 s[18:19], s[6:7], 20
	s_add_u32 s18, s38, s18
	s_addc_u32 s19, s39, s19
	s_and_b64 s[26:27], vcc, exec
	s_cselect_b32 s7, s19, s25
	s_cselect_b32 s58, s18, s24
	s_add_u32 s22, s22, 0x80080
	s_addc_u32 s23, s23, 0
	s_add_u32 s59, s24, 0x100
	v_mov_b32_e32 v2, 0
	s_addc_u32 s60, s25, 0
	s_mov_b32 s61, -2
	v_mov_b32_e32 v3, v2
	v_mov_b32_e32 v4, v2
	v_mov_b32_e32 v5, v2
	v_mov_b32_e32 v6, v2
	v_mov_b32_e32 v7, v2
	v_mov_b32_e32 v8, v2
	v_mov_b32_e32 v9, v2
	v_mov_b32_e32 v10, v2
	v_mov_b32_e32 v11, v2
	v_mov_b32_e32 v12, v2
	v_mov_b32_e32 v13, v2
	v_mov_b32_e32 v18, v2
	v_mov_b32_e32 v19, v2
	v_mov_b32_e32 v20, v2
	v_mov_b32_e32 v21, v2
	v_mov_b32_e32 v26, v2
	v_mov_b32_e32 v27, v2
	v_mov_b32_e32 v28, v2
	v_mov_b32_e32 v29, v2
	v_mov_b32_e32 v34, v2
	v_mov_b32_e32 v35, v2
	v_mov_b32_e32 v36, v2
	v_mov_b32_e32 v37, v2
	v_mov_b32_e32 v42, v2
	v_mov_b32_e32 v43, v2
	v_mov_b32_e32 v44, v2
	v_mov_b32_e32 v45, v2
	v_mov_b32_e32 v50, v2
	v_mov_b32_e32 v51, v2
	v_mov_b32_e32 v52, v2
	v_mov_b32_e32 v53, v2
	v_mov_b32_e32 v14, v2
	v_mov_b32_e32 v15, v2
	v_mov_b32_e32 v16, v2
	v_mov_b32_e32 v17, v2
	v_mov_b32_e32 v22, v2
	v_mov_b32_e32 v23, v2
	v_mov_b32_e32 v24, v2
	v_mov_b32_e32 v25, v2
	v_mov_b32_e32 v30, v2
	v_mov_b32_e32 v31, v2
	v_mov_b32_e32 v32, v2
	v_mov_b32_e32 v33, v2
	v_mov_b32_e32 v38, v2
	v_mov_b32_e32 v39, v2
	v_mov_b32_e32 v40, v2
	v_mov_b32_e32 v41, v2
	v_mov_b32_e32 v46, v2
	v_mov_b32_e32 v47, v2
	v_mov_b32_e32 v48, v2
	v_mov_b32_e32 v49, v2
	v_mov_b32_e32 v54, v2
	v_mov_b32_e32 v55, v2
	v_mov_b32_e32 v56, v2
	v_mov_b32_e32 v57, v2
	v_mov_b32_e32 v58, v2
	v_mov_b32_e32 v59, v2
	v_mov_b32_e32 v60, v2
	v_mov_b32_e32 v61, v2
	v_mov_b32_e32 v62, v2
	v_mov_b32_e32 v63, v2
	v_mov_b32_e32 v64, v2
	v_mov_b32_e32 v65, v2
	v_mov_b32_e32 v66, v2
	v_mov_b32_e32 v67, v2
	v_mov_b32_e32 v68, v2
	v_mov_b32_e32 v69, v2
	v_mov_b32_e32 v70, v2
	v_mov_b32_e32 v71, v2
	v_mov_b32_e32 v72, v2
	v_mov_b32_e32 v73, v2
	v_mov_b32_e32 v74, v2
	v_mov_b32_e32 v75, v2
	v_mov_b32_e32 v76, v2
	v_mov_b32_e32 v77, v2
	v_mov_b32_e32 v82, v2
	v_mov_b32_e32 v83, v2
	v_mov_b32_e32 v84, v2
	v_mov_b32_e32 v85, v2
	v_mov_b32_e32 v90, v2
	v_mov_b32_e32 v91, v2
	v_mov_b32_e32 v92, v2
	v_mov_b32_e32 v93, v2
	v_mov_b32_e32 v98, v2
	v_mov_b32_e32 v99, v2
	v_mov_b32_e32 v100, v2
	v_mov_b32_e32 v101, v2
	v_mov_b32_e32 v106, v2
	v_mov_b32_e32 v107, v2
	v_mov_b32_e32 v108, v2
	v_mov_b32_e32 v109, v2
	v_mov_b32_e32 v114, v2
	v_mov_b32_e32 v115, v2
	v_mov_b32_e32 v116, v2
	v_mov_b32_e32 v117, v2
	v_mov_b32_e32 v78, v2
	v_mov_b32_e32 v79, v2
	v_mov_b32_e32 v80, v2
	v_mov_b32_e32 v81, v2
	v_mov_b32_e32 v86, v2
	v_mov_b32_e32 v87, v2
	v_mov_b32_e32 v88, v2
	v_mov_b32_e32 v89, v2
	v_mov_b32_e32 v94, v2
	v_mov_b32_e32 v95, v2
	v_mov_b32_e32 v96, v2
	v_mov_b32_e32 v97, v2
	v_mov_b32_e32 v102, v2
	v_mov_b32_e32 v103, v2
	v_mov_b32_e32 v104, v2
	v_mov_b32_e32 v105, v2
	v_mov_b32_e32 v110, v2
	v_mov_b32_e32 v111, v2
	v_mov_b32_e32 v112, v2
	v_mov_b32_e32 v113, v2
	v_mov_b32_e32 v118, v2
	v_mov_b32_e32 v119, v2
	v_mov_b32_e32 v120, v2
	v_mov_b32_e32 v121, v2
	v_mov_b32_e32 v122, v2
	v_mov_b32_e32 v123, v2
	v_mov_b32_e32 v124, v2
	v_mov_b32_e32 v125, v2
	v_mov_b32_e32 v126, v2
	v_mov_b32_e32 v127, v2
	v_mov_b32_e32 v128, v2
	v_mov_b32_e32 v129, v2
	s_cmp_eq_u32 s98, 0
	s_cbranch_scc1 .LBB0_269
	ds_read_b128 v[146:149], v152
	ds_read_b128 v[156:159], v152 offset:1024
	ds_read_b128 v[160:163], v152 offset:2048
	ds_read_b128 v[164:167], v152 offset:3072
	s_add_u32 s24, s22, 0xfff80080
	s_addc_u32 s25, s23, -1
	s_cmp_eq_u32 s61, 28
	s_cselect_b32 s27, s9, s25
	s_cselect_b32 s26, s53, s24
	s_cselect_b32 s25, s7, s60
	s_cselect_b32 s24, s58, s59
	s_add_i32 m0, s21, 0xc000
	ds_read_b128 v[168:171], v153
	ds_read_b128 v[172:175], v153 offset:1024
	ds_read_b128 v[176:179], v153 offset:2048
	ds_read_b128 v[180:183], v153 offset:3072
	ds_read_b128 v[186:189], v153 offset:4096
	ds_read_b128 v[190:193], v153 offset:5120
	ds_read_b128 v[194:197], v153 offset:6144
	ds_read_b128 v[198:201], v153 offset:7168
	ds_read_b128 v[202:205], v154
	ds_read_b128 v[206:209], v154 offset:1024
	ds_read_b128 v[210:213], v154 offset:2048
	ds_read_b128 v[214:217], v154 offset:3072
	global_load_lds_dwordx4 v138, s[22:23]
	s_add_i32 m0, s21, 0xe000
	s_nop 0
	global_load_lds_dwordx4 v140, s[22:23]
	s_waitcnt vmcnt(24)
	s_waitcnt lgkmcnt(0)
	s_barrier
	s_setprio 1
	v_mfma_f32_16x16x32_bf16 v[126:129], v[146:149], v[168:171], v[126:129]
	v_mfma_f32_16x16x32_bf16 v[122:125], v[160:163], v[168:171], v[122:125]
	v_mfma_f32_16x16x32_bf16 v[118:121], v[146:149], v[176:179], v[118:121]
	v_mfma_f32_16x16x32_bf16 v[110:113], v[160:163], v[176:179], v[110:113]
	v_mfma_f32_16x16x32_bf16 v[102:105], v[146:149], v[186:189], v[102:105]
	v_mfma_f32_16x16x32_bf16 v[94:97], v[160:163], v[186:189], v[94:97]
	v_mfma_f32_16x16x32_bf16 v[86:89], v[146:149], v[194:197], v[86:89]
	v_mfma_f32_16x16x32_bf16 v[78:81], v[160:163], v[194:197], v[78:81]
	v_mfma_f32_16x16x32_bf16 v[126:129], v[156:159], v[172:175], v[126:129]
	v_mfma_f32_16x16x32_bf16 v[122:125], v[164:167], v[172:175], v[122:125]
	v_mfma_f32_16x16x32_bf16 v[118:121], v[156:159], v[180:183], v[118:121]
	v_mfma_f32_16x16x32_bf16 v[110:113], v[164:167], v[180:183], v[110:113]
	v_mfma_f32_16x16x32_bf16 v[102:105], v[156:159], v[190:193], v[102:105]
	v_mfma_f32_16x16x32_bf16 v[94:97], v[164:167], v[190:193], v[94:97]
	v_mfma_f32_16x16x32_bf16 v[86:89], v[156:159], v[198:201], v[86:89]
	v_mfma_f32_16x16x32_bf16 v[78:81], v[164:167], v[198:201], v[78:81]
	v_mfma_f32_16x16x32_bf16 v[114:117], v[202:205], v[168:171], v[114:117]
	v_mfma_f32_16x16x32_bf16 v[106:109], v[210:213], v[168:171], v[106:109]
	v_mfma_f32_16x16x32_bf16 v[98:101], v[202:205], v[176:179], v[98:101]
	v_mfma_f32_16x16x32_bf16 v[90:93], v[210:213], v[176:179], v[90:93]
	v_mfma_f32_16x16x32_bf16 v[82:85], v[202:205], v[186:189], v[82:85]
	v_mfma_f32_16x16x32_bf16 v[74:77], v[210:213], v[186:189], v[74:77]
	v_mfma_f32_16x16x32_bf16 v[70:73], v[202:205], v[194:197], v[70:73]
	v_mfma_f32_16x16x32_bf16 v[66:69], v[210:213], v[194:197], v[66:69]
	v_mfma_f32_16x16x32_bf16 v[114:117], v[206:209], v[172:175], v[114:117]
	v_mfma_f32_16x16x32_bf16 v[106:109], v[214:217], v[172:175], v[106:109]
	v_mfma_f32_16x16x32_bf16 v[98:101], v[206:209], v[180:183], v[98:101]
	v_mfma_f32_16x16x32_bf16 v[90:93], v[214:217], v[180:183], v[90:93]
	v_mfma_f32_16x16x32_bf16 v[82:85], v[206:209], v[190:193], v[82:85]
	v_mfma_f32_16x16x32_bf16 v[74:77], v[214:217], v[190:193], v[74:77]
	v_mfma_f32_16x16x32_bf16 v[70:73], v[206:209], v[198:201], v[70:73]
	v_mfma_f32_16x16x32_bf16 v[66:69], v[214:217], v[198:201], v[66:69]
	s_setprio 0
	s_barrier
	s_add_i32 s68, s45, s29
	v_lshl_add_u64 v[218:219], s[24:25], 0, v[134:135]
	s_mov_b32 m0, s68
	global_load_lds_dwordx4 v134, s[24:25]
	v_lshl_add_u64 v[220:221], s[24:25], 0, v[130:131]
	s_add_i32 m0, s68, 0x2000
	s_nop 0
	global_load_lds_dwordx4 v130, s[24:25]
	s_mov_b32 m0, s21
	v_lshl_add_u64 v[222:223], s[26:27], 0, v[136:137]
	ds_read_b128 v[168:171], v153 offset:16384
	ds_read_b128 v[172:175], v153 offset:17408
	ds_read_b128 v[176:179], v153 offset:18432
	ds_read_b128 v[180:183], v153 offset:19456
	ds_read_b128 v[186:189], v153 offset:20480
	ds_read_b128 v[190:193], v153 offset:21504
	ds_read_b128 v[194:197], v153 offset:22528
	ds_read_b128 v[198:201], v153 offset:23552
	global_load_lds_dwordx4 v136, s[26:27]
	v_lshl_add_u64 v[224:225], s[26:27], 0, v[132:133]
	s_mov_b32 m0, s34
	s_nop 0
	global_load_lds_dwordx4 v132, s[26:27]
	s_waitcnt vmcnt(22)
	s_waitcnt lgkmcnt(0)
	s_barrier
	s_setprio 1
	v_mfma_f32_16x16x32_bf16 v[62:65], v[146:149], v[168:171], v[62:65]
	v_mfma_f32_16x16x32_bf16 v[58:61], v[160:163], v[168:171], v[58:61]
	v_mfma_f32_16x16x32_bf16 v[54:57], v[146:149], v[176:179], v[54:57]
	v_mfma_f32_16x16x32_bf16 v[46:49], v[160:163], v[176:179], v[46:49]
	v_mfma_f32_16x16x32_bf16 v[38:41], v[146:149], v[186:189], v[38:41]
	v_mfma_f32_16x16x32_bf16 v[30:33], v[160:163], v[186:189], v[30:33]
	v_mfma_f32_16x16x32_bf16 v[22:25], v[146:149], v[194:197], v[22:25]
	v_mfma_f32_16x16x32_bf16 v[14:17], v[160:163], v[194:197], v[14:17]
	v_mfma_f32_16x16x32_bf16 v[62:65], v[156:159], v[172:175], v[62:65]
	v_mfma_f32_16x16x32_bf16 v[58:61], v[164:167], v[172:175], v[58:61]
	v_mfma_f32_16x16x32_bf16 v[54:57], v[156:159], v[180:183], v[54:57]
	v_mfma_f32_16x16x32_bf16 v[46:49], v[164:167], v[180:183], v[46:49]
	v_mfma_f32_16x16x32_bf16 v[38:41], v[156:159], v[190:193], v[38:41]
	v_mfma_f32_16x16x32_bf16 v[30:33], v[164:167], v[190:193], v[30:33]
	v_mfma_f32_16x16x32_bf16 v[22:25], v[156:159], v[198:201], v[22:25]
	v_mfma_f32_16x16x32_bf16 v[14:17], v[164:167], v[198:201], v[14:17]
	v_mfma_f32_16x16x32_bf16 v[50:53], v[202:205], v[168:171], v[50:53]
	v_mfma_f32_16x16x32_bf16 v[42:45], v[210:213], v[168:171], v[42:45]
	v_mfma_f32_16x16x32_bf16 v[34:37], v[202:205], v[176:179], v[34:37]
	v_mfma_f32_16x16x32_bf16 v[26:29], v[210:213], v[176:179], v[26:29]
	v_mfma_f32_16x16x32_bf16 v[18:21], v[202:205], v[186:189], v[18:21]
	v_mfma_f32_16x16x32_bf16 v[10:13], v[210:213], v[186:189], v[10:13]
	v_mfma_f32_16x16x32_bf16 v[6:9], v[202:205], v[194:197], v[6:9]
	v_mfma_f32_16x16x32_bf16 v[2:5], v[210:213], v[194:197], v[2:5]
	v_mfma_f32_16x16x32_bf16 v[50:53], v[206:209], v[172:175], v[50:53]
	v_mfma_f32_16x16x32_bf16 v[42:45], v[214:217], v[172:175], v[42:45]
	v_mfma_f32_16x16x32_bf16 v[34:37], v[206:209], v[180:183], v[34:37]
	v_mfma_f32_16x16x32_bf16 v[26:29], v[214:217], v[180:183], v[26:29]
	v_mfma_f32_16x16x32_bf16 v[18:21], v[206:209], v[190:193], v[18:21]
	v_mfma_f32_16x16x32_bf16 v[10:13], v[214:217], v[190:193], v[10:13]
	v_mfma_f32_16x16x32_bf16 v[6:9], v[206:209], v[198:201], v[6:9]
	v_mfma_f32_16x16x32_bf16 v[2:5], v[214:217], v[198:201], v[2:5]
	s_setprio 0
	s_barrier
	s_add_u32 s68, s24, 0x80000
	s_addc_u32 s69, s25, 0
	s_add_i32 s70, s46, s29
	s_mov_b32 m0, s70
	s_nop 0
	global_load_lds_dwordx4 v134, s[68:69]
	s_add_i32 m0, s70, 0x2000
	s_nop 0
	global_load_lds_dwordx4 v130, s[68:69]
	s_add_i32 s68, 0, 0x18000
	v_add_u32_e32 v155, s68, v150
	ds_read_b128 v[146:149], v155
	ds_read_b128 v[156:159], v155 offset:1024
	ds_read_b128 v[160:163], v155 offset:2048
	ds_read_b128 v[164:167], v155 offset:3072
	s_add_u32 s26, s26, 0x80000
	s_addc_u32 s27, s27, 0
	s_mov_b32 m0, s35
	ds_read_b128 v[168:171], v153 offset:32768
	ds_read_b128 v[172:175], v153 offset:33792
	ds_read_b128 v[176:179], v153 offset:34816
	ds_read_b128 v[180:183], v153 offset:35840
	ds_read_b128 v[186:189], v153 offset:36864
	ds_read_b128 v[190:193], v153 offset:37888
	ds_read_b128 v[194:197], v153 offset:38912
	ds_read_b128 v[198:201], v153 offset:39936
	v_add_u32_e32 v214, 0x1c000, v150
	ds_read_b128 v[202:205], v214
	ds_read_b128 v[206:209], v214 offset:1024
	ds_read_b128 v[210:213], v214 offset:2048
	ds_read_b128 v[214:217], v214 offset:3072
	global_load_lds_dwordx4 v136, s[26:27]
	s_mov_b32 m0, s36
	s_nop 0
	global_load_lds_dwordx4 v132, s[26:27]
	s_waitcnt vmcnt(8)
	s_waitcnt lgkmcnt(0)
	s_barrier
	s_setprio 1
	v_mfma_f32_16x16x32_bf16 v[126:129], v[146:149], v[168:171], v[126:129]
	v_mfma_f32_16x16x32_bf16 v[122:125], v[160:163], v[168:171], v[122:125]
	v_mfma_f32_16x16x32_bf16 v[118:121], v[146:149], v[176:179], v[118:121]
	v_mfma_f32_16x16x32_bf16 v[110:113], v[160:163], v[176:179], v[110:113]
	v_mfma_f32_16x16x32_bf16 v[102:105], v[146:149], v[186:189], v[102:105]
	v_mfma_f32_16x16x32_bf16 v[94:97], v[160:163], v[186:189], v[94:97]
	v_mfma_f32_16x16x32_bf16 v[86:89], v[146:149], v[194:197], v[86:89]
	v_mfma_f32_16x16x32_bf16 v[78:81], v[160:163], v[194:197], v[78:81]
	v_mfma_f32_16x16x32_bf16 v[126:129], v[156:159], v[172:175], v[126:129]
	v_mfma_f32_16x16x32_bf16 v[122:125], v[164:167], v[172:175], v[122:125]
	v_mfma_f32_16x16x32_bf16 v[118:121], v[156:159], v[180:183], v[118:121]
	v_mfma_f32_16x16x32_bf16 v[110:113], v[164:167], v[180:183], v[110:113]
	v_mfma_f32_16x16x32_bf16 v[102:105], v[156:159], v[190:193], v[102:105]
	v_mfma_f32_16x16x32_bf16 v[94:97], v[164:167], v[190:193], v[94:97]
	v_mfma_f32_16x16x32_bf16 v[86:89], v[156:159], v[198:201], v[86:89]
	v_mfma_f32_16x16x32_bf16 v[78:81], v[164:167], v[198:201], v[78:81]
	v_mfma_f32_16x16x32_bf16 v[114:117], v[202:205], v[168:171], v[114:117]
	v_mfma_f32_16x16x32_bf16 v[106:109], v[210:213], v[168:171], v[106:109]
	v_mfma_f32_16x16x32_bf16 v[98:101], v[202:205], v[176:179], v[98:101]
	v_mfma_f32_16x16x32_bf16 v[90:93], v[210:213], v[176:179], v[90:93]
	v_mfma_f32_16x16x32_bf16 v[82:85], v[202:205], v[186:189], v[82:85]
	v_mfma_f32_16x16x32_bf16 v[74:77], v[210:213], v[186:189], v[74:77]
	v_mfma_f32_16x16x32_bf16 v[70:73], v[202:205], v[194:197], v[70:73]
	v_mfma_f32_16x16x32_bf16 v[66:69], v[210:213], v[194:197], v[66:69]
	v_mfma_f32_16x16x32_bf16 v[114:117], v[206:209], v[172:175], v[114:117]
	v_mfma_f32_16x16x32_bf16 v[106:109], v[214:217], v[172:175], v[106:109]
	v_mfma_f32_16x16x32_bf16 v[98:101], v[206:209], v[180:183], v[98:101]
	v_mfma_f32_16x16x32_bf16 v[90:93], v[214:217], v[180:183], v[90:93]
	v_mfma_f32_16x16x32_bf16 v[82:85], v[206:209], v[190:193], v[82:85]
	v_mfma_f32_16x16x32_bf16 v[74:77], v[214:217], v[190:193], v[74:77]
	v_mfma_f32_16x16x32_bf16 v[70:73], v[206:209], v[198:201], v[70:73]
	v_mfma_f32_16x16x32_bf16 v[66:69], v[214:217], v[198:201], v[66:69]
	s_setprio 0
	s_barrier
	s_add_i32 s26, 0, 0x1c000
	s_add_i32 s27, s68, s29
	v_lshl_add_u64 v[218:219], v[218:219], 0, s[4:5]
	s_mov_b32 m0, s27
	global_load_lds_dwordx4 v[218:219], off
	v_lshl_add_u64 v[218:219], v[220:221], 0, s[4:5]
	s_add_i32 m0, s27, 0x2000
	s_nop 0
	global_load_lds_dwordx4 v[218:219], off
	s_mov_b32 m0, s41
	v_lshl_add_u64 v[218:219], v[222:223], 0, s[4:5]
	ds_read_b128 v[168:171], v153 offset:49152
	ds_read_b128 v[172:175], v153 offset:50176
	ds_read_b128 v[176:179], v153 offset:51200
	ds_read_b128 v[180:183], v153 offset:52224
	ds_read_b128 v[186:189], v153 offset:53248
	ds_read_b128 v[190:193], v153 offset:54272
	ds_read_b128 v[194:197], v153 offset:55296
	ds_read_b128 v[198:201], v153 offset:56320
	global_load_lds_dwordx4 v[218:219], off
	v_lshl_add_u64 v[218:219], v[224:225], 0, s[4:5]
	s_mov_b32 m0, s42
	s_nop 0
	global_load_lds_dwordx4 v[218:219], off
	s_add_u32 s24, s24, 0x80080
	s_addc_u32 s25, s25, 0
	s_add_i32 s26, s26, s29
	s_mov_b32 m0, s26
	s_nop 0
	global_load_lds_dwordx4 v134, s[24:25]
	s_add_i32 m0, s26, 0x2000
	s_nop 0
	global_load_lds_dwordx4 v130, s[24:25]
	s_waitcnt vmcnt(8)
	s_waitcnt lgkmcnt(0)
	s_barrier
	s_setprio 1
	v_mfma_f32_16x16x32_bf16 v[62:65], v[146:149], v[168:171], v[62:65]
	v_mfma_f32_16x16x32_bf16 v[58:61], v[160:163], v[168:171], v[58:61]
	v_mfma_f32_16x16x32_bf16 v[54:57], v[146:149], v[176:179], v[54:57]
	v_mfma_f32_16x16x32_bf16 v[46:49], v[160:163], v[176:179], v[46:49]
	v_mfma_f32_16x16x32_bf16 v[38:41], v[146:149], v[186:189], v[38:41]
	v_mfma_f32_16x16x32_bf16 v[30:33], v[160:163], v[186:189], v[30:33]
	v_mfma_f32_16x16x32_bf16 v[22:25], v[146:149], v[194:197], v[22:25]
	v_mfma_f32_16x16x32_bf16 v[14:17], v[160:163], v[194:197], v[14:17]
	v_mfma_f32_16x16x32_bf16 v[62:65], v[156:159], v[172:175], v[62:65]
	v_mfma_f32_16x16x32_bf16 v[58:61], v[164:167], v[172:175], v[58:61]
	v_mfma_f32_16x16x32_bf16 v[54:57], v[156:159], v[180:183], v[54:57]
	v_mfma_f32_16x16x32_bf16 v[46:49], v[164:167], v[180:183], v[46:49]
	v_mfma_f32_16x16x32_bf16 v[38:41], v[156:159], v[190:193], v[38:41]
	v_mfma_f32_16x16x32_bf16 v[30:33], v[164:167], v[190:193], v[30:33]
	v_mfma_f32_16x16x32_bf16 v[22:25], v[156:159], v[198:201], v[22:25]
	v_mfma_f32_16x16x32_bf16 v[14:17], v[164:167], v[198:201], v[14:17]
	v_mfma_f32_16x16x32_bf16 v[50:53], v[202:205], v[168:171], v[50:53]
	v_mfma_f32_16x16x32_bf16 v[42:45], v[210:213], v[168:171], v[42:45]
	v_mfma_f32_16x16x32_bf16 v[34:37], v[202:205], v[176:179], v[34:37]
	v_mfma_f32_16x16x32_bf16 v[26:29], v[210:213], v[176:179], v[26:29]
	v_mfma_f32_16x16x32_bf16 v[18:21], v[202:205], v[186:189], v[18:21]
	v_mfma_f32_16x16x32_bf16 v[10:13], v[210:213], v[186:189], v[10:13]
	v_mfma_f32_16x16x32_bf16 v[6:9], v[202:205], v[194:197], v[6:9]
	v_mfma_f32_16x16x32_bf16 v[2:5], v[210:213], v[194:197], v[2:5]
	v_mfma_f32_16x16x32_bf16 v[50:53], v[206:209], v[172:175], v[50:53]
	v_mfma_f32_16x16x32_bf16 v[42:45], v[214:217], v[172:175], v[42:45]
	v_mfma_f32_16x16x32_bf16 v[34:37], v[206:209], v[180:183], v[34:37]
	v_mfma_f32_16x16x32_bf16 v[26:29], v[214:217], v[180:183], v[26:29]
	v_mfma_f32_16x16x32_bf16 v[18:21], v[206:209], v[190:193], v[18:21]
	v_mfma_f32_16x16x32_bf16 v[10:13], v[214:217], v[190:193], v[10:13]
	v_mfma_f32_16x16x32_bf16 v[6:9], v[206:209], v[198:201], v[6:9]
	v_mfma_f32_16x16x32_bf16 v[2:5], v[214:217], v[198:201], v[2:5]
	s_setprio 0
	s_add_i32 s61, s61, 2
	s_add_u32 s22, s22, 0x100
	s_addc_u32 s23, s23, 0
	s_add_u32 s59, s59, 0x100
	s_addc_u32 s60, s60, 0
	s_cmp_gt_u32 s61, 29
	s_barrier
	s_cbranch_scc1 .Lgemm_epi_0

.LBB0_456:
	s_ashr_i32 s23, s22, 31
	s_lshl_b64 s[26:27], s[22:23], 18
	s_add_u32 s26, s43, s26
	s_addc_u32 s27, s44, s27
	s_and_b64 s[4:5], s[4:5], exec
	s_cselect_b32 s23, s27, s31
	s_cselect_b32 s78, s26, s30
	s_add_u32 s79, s30, 0x100
	v_mov_b32_e32 v2, 0
	s_addc_u32 s80, s31, 0
	s_mov_b32 s81, -2
	v_mov_b32_e32 v3, v2
	v_mov_b32_e32 v4, v2
	v_mov_b32_e32 v5, v2
	v_mov_b32_e32 v6, v2
	v_mov_b32_e32 v7, v2
	v_mov_b32_e32 v8, v2
	v_mov_b32_e32 v9, v2
	v_mov_b32_e32 v10, v2
	v_mov_b32_e32 v11, v2
	v_mov_b32_e32 v12, v2
	v_mov_b32_e32 v13, v2
	v_mov_b32_e32 v18, v2
	v_mov_b32_e32 v19, v2
	v_mov_b32_e32 v20, v2
	v_mov_b32_e32 v21, v2
	v_mov_b32_e32 v26, v2
	v_mov_b32_e32 v27, v2
	v_mov_b32_e32 v28, v2
	v_mov_b32_e32 v29, v2
	v_mov_b32_e32 v34, v2
	v_mov_b32_e32 v35, v2
	v_mov_b32_e32 v36, v2
	v_mov_b32_e32 v37, v2
	v_mov_b32_e32 v42, v2
	v_mov_b32_e32 v43, v2
	v_mov_b32_e32 v44, v2
	v_mov_b32_e32 v45, v2
	v_mov_b32_e32 v50, v2
	v_mov_b32_e32 v51, v2
	v_mov_b32_e32 v52, v2
	v_mov_b32_e32 v53, v2
	v_mov_b32_e32 v14, v2
	v_mov_b32_e32 v15, v2
	v_mov_b32_e32 v16, v2
	v_mov_b32_e32 v17, v2
	v_mov_b32_e32 v22, v2
	v_mov_b32_e32 v23, v2
	v_mov_b32_e32 v24, v2
	v_mov_b32_e32 v25, v2
	v_mov_b32_e32 v30, v2
	v_mov_b32_e32 v31, v2
	v_mov_b32_e32 v32, v2
	v_mov_b32_e32 v33, v2
	v_mov_b32_e32 v38, v2
	v_mov_b32_e32 v39, v2
	v_mov_b32_e32 v40, v2
	v_mov_b32_e32 v41, v2
	v_mov_b32_e32 v46, v2
	v_mov_b32_e32 v47, v2
	v_mov_b32_e32 v48, v2
	v_mov_b32_e32 v49, v2
	v_mov_b32_e32 v54, v2
	v_mov_b32_e32 v55, v2
	v_mov_b32_e32 v56, v2
	v_mov_b32_e32 v57, v2
	v_mov_b32_e32 v58, v2
	v_mov_b32_e32 v59, v2
	v_mov_b32_e32 v60, v2
	v_mov_b32_e32 v61, v2
	v_mov_b32_e32 v62, v2
	v_mov_b32_e32 v63, v2
	v_mov_b32_e32 v64, v2
	v_mov_b32_e32 v65, v2
	v_mov_b32_e32 v66, v2
	v_mov_b32_e32 v67, v2
	v_mov_b32_e32 v68, v2
	v_mov_b32_e32 v69, v2
	v_mov_b32_e32 v70, v2
	v_mov_b32_e32 v71, v2
	v_mov_b32_e32 v72, v2
	v_mov_b32_e32 v73, v2
	v_mov_b32_e32 v78, v2
	v_mov_b32_e32 v79, v2
	v_mov_b32_e32 v80, v2
	v_mov_b32_e32 v81, v2
	v_mov_b32_e32 v86, v2
	v_mov_b32_e32 v87, v2
	v_mov_b32_e32 v88, v2
	v_mov_b32_e32 v89, v2
	v_mov_b32_e32 v94, v2
	v_mov_b32_e32 v95, v2
	v_mov_b32_e32 v96, v2
	v_mov_b32_e32 v97, v2
	v_mov_b32_e32 v102, v2
	v_mov_b32_e32 v103, v2
	v_mov_b32_e32 v104, v2
	v_mov_b32_e32 v105, v2
	v_mov_b32_e32 v110, v2
	v_mov_b32_e32 v111, v2
	v_mov_b32_e32 v112, v2
	v_mov_b32_e32 v113, v2
	v_mov_b32_e32 v118, v2
	v_mov_b32_e32 v119, v2
	v_mov_b32_e32 v120, v2
	v_mov_b32_e32 v121, v2
	v_mov_b32_e32 v74, v2
	v_mov_b32_e32 v75, v2
	v_mov_b32_e32 v76, v2
	v_mov_b32_e32 v77, v2
	v_mov_b32_e32 v82, v2
	v_mov_b32_e32 v83, v2
	v_mov_b32_e32 v84, v2
	v_mov_b32_e32 v85, v2
	v_mov_b32_e32 v90, v2
	v_mov_b32_e32 v91, v2
	v_mov_b32_e32 v92, v2
	v_mov_b32_e32 v93, v2
	v_mov_b32_e32 v98, v2
	v_mov_b32_e32 v99, v2
	v_mov_b32_e32 v100, v2
	v_mov_b32_e32 v101, v2
	v_mov_b32_e32 v106, v2
	v_mov_b32_e32 v107, v2
	v_mov_b32_e32 v108, v2
	v_mov_b32_e32 v109, v2
	v_mov_b32_e32 v114, v2
	v_mov_b32_e32 v115, v2
	v_mov_b32_e32 v116, v2
	v_mov_b32_e32 v117, v2
	v_mov_b32_e32 v122, v2
	v_mov_b32_e32 v123, v2
	v_mov_b32_e32 v124, v2
	v_mov_b32_e32 v125, v2
	v_mov_b32_e32 v126, v2
	v_mov_b32_e32 v127, v2
	v_mov_b32_e32 v128, v2
	v_mov_b32_e32 v129, v2
	s_cmp_eq_u32 s98, 0
	s_cbranch_scc1 .LBB0_457
	ds_read_b128 v[154:157], v150
	ds_read_b128 v[158:161], v150 offset:1024
	ds_read_b128 v[162:165], v150 offset:2048
	ds_read_b128 v[166:169], v150 offset:3072
	s_add_u32 s4, s28, 0x100
	s_addc_u32 s5, s29, 0
	s_cmp_eq_u32 s81, 4
	s_cselect_b32 s35, s25, s5
	s_cselect_b32 s34, s24, s4
	s_cselect_b32 s31, s23, s80
	s_cselect_b32 s30, s78, s79
	v_lshl_add_u64 v[146:147], s[28:29], 0, v[138:139]
	s_add_i32 m0, s46, 0xc000
	ds_read_b128 v[170:173], v151
	ds_read_b128 v[174:177], v151 offset:1024
	ds_read_b128 v[178:181], v151 offset:2048
	ds_read_b128 v[186:189], v151 offset:3072
	ds_read_b128 v[190:193], v151 offset:4096
	ds_read_b128 v[194:197], v151 offset:5120
	ds_read_b128 v[198:201], v151 offset:6144
	ds_read_b128 v[202:205], v151 offset:7168
	global_load_lds_dwordx4 v[146:147], off
	v_lshl_add_u64 v[146:147], s[28:29], 0, v[140:141]
	s_add_i32 m0, s46, 0xe000
	s_nop 0
	global_load_lds_dwordx4 v[146:147], off
	ds_read_b128 v[206:209], v152
	ds_read_b128 v[210:213], v152 offset:1024
	ds_read_b128 v[214:217], v152 offset:2048
	ds_read_b128 v[218:221], v152 offset:3072
	s_waitcnt vmcnt(24)
	s_waitcnt lgkmcnt(0)
	s_barrier
	s_setprio 1
	v_mfma_f32_16x16x32_bf16 v[126:129], v[154:157], v[170:173], v[126:129]
	v_mfma_f32_16x16x32_bf16 v[122:125], v[162:165], v[170:173], v[122:125]
	v_mfma_f32_16x16x32_bf16 v[114:117], v[154:157], v[178:181], v[114:117]
	v_mfma_f32_16x16x32_bf16 v[106:109], v[162:165], v[178:181], v[106:109]
	v_mfma_f32_16x16x32_bf16 v[98:101], v[154:157], v[190:193], v[98:101]
	v_mfma_f32_16x16x32_bf16 v[90:93], v[162:165], v[190:193], v[90:93]
	v_mfma_f32_16x16x32_bf16 v[82:85], v[154:157], v[198:201], v[82:85]
	v_mfma_f32_16x16x32_bf16 v[74:77], v[162:165], v[198:201], v[74:77]
	v_mfma_f32_16x16x32_bf16 v[126:129], v[158:161], v[174:177], v[126:129]
	v_mfma_f32_16x16x32_bf16 v[122:125], v[166:169], v[174:177], v[122:125]
	v_mfma_f32_16x16x32_bf16 v[114:117], v[158:161], v[186:189], v[114:117]
	v_mfma_f32_16x16x32_bf16 v[106:109], v[166:169], v[186:189], v[106:109]
	v_mfma_f32_16x16x32_bf16 v[98:101], v[158:161], v[194:197], v[98:101]
	v_mfma_f32_16x16x32_bf16 v[90:93], v[166:169], v[194:197], v[90:93]
	v_mfma_f32_16x16x32_bf16 v[82:85], v[158:161], v[202:205], v[82:85]
	v_mfma_f32_16x16x32_bf16 v[74:77], v[166:169], v[202:205], v[74:77]
	v_mfma_f32_16x16x32_bf16 v[118:121], v[206:209], v[170:173], v[118:121]
	v_mfma_f32_16x16x32_bf16 v[110:113], v[214:217], v[170:173], v[110:113]
	v_mfma_f32_16x16x32_bf16 v[102:105], v[206:209], v[178:181], v[102:105]
	v_mfma_f32_16x16x32_bf16 v[94:97], v[214:217], v[178:181], v[94:97]
	v_mfma_f32_16x16x32_bf16 v[86:89], v[206:209], v[190:193], v[86:89]
	v_mfma_f32_16x16x32_bf16 v[78:81], v[214:217], v[190:193], v[78:81]
	v_mfma_f32_16x16x32_bf16 v[70:73], v[206:209], v[198:201], v[70:73]
	v_mfma_f32_16x16x32_bf16 v[66:69], v[214:217], v[198:201], v[66:69]
	v_mfma_f32_16x16x32_bf16 v[118:121], v[210:213], v[174:177], v[118:121]
	v_mfma_f32_16x16x32_bf16 v[110:113], v[218:221], v[174:177], v[110:113]
	v_mfma_f32_16x16x32_bf16 v[102:105], v[210:213], v[186:189], v[102:105]
	v_mfma_f32_16x16x32_bf16 v[94:97], v[218:221], v[186:189], v[94:97]
	v_mfma_f32_16x16x32_bf16 v[86:89], v[210:213], v[194:197], v[86:89]
	v_mfma_f32_16x16x32_bf16 v[78:81], v[218:221], v[194:197], v[78:81]
	v_mfma_f32_16x16x32_bf16 v[70:73], v[210:213], v[202:205], v[70:73]
	v_mfma_f32_16x16x32_bf16 v[66:69], v[218:221], v[202:205], v[66:69]
	s_setprio 0
	s_barrier
	s_add_i32 s28, s61, s45
	v_lshl_add_u64 v[146:147], s[30:31], 0, v[132:133]
	s_mov_b32 m0, s28
	global_load_lds_dwordx4 v132, s[30:31]
	v_lshl_add_u64 v[182:183], s[30:31], 0, v[136:137]
	s_add_i32 m0, s28, 0x2000
	s_nop 0
	global_load_lds_dwordx4 v136, s[30:31]
	s_mov_b32 m0, s46
	v_lshl_add_u64 v[222:223], s[34:35], 0, v[130:131]
	ds_read_b128 v[170:173], v151 offset:16384
	ds_read_b128 v[174:177], v151 offset:17408
	ds_read_b128 v[178:181], v151 offset:18432
	ds_read_b128 v[186:189], v151 offset:19456
	ds_read_b128 v[190:193], v151 offset:20480
	ds_read_b128 v[194:197], v151 offset:21504
	ds_read_b128 v[198:201], v151 offset:22528
	ds_read_b128 v[202:205], v151 offset:23552
	global_load_lds_dwordx4 v130, s[34:35]
	v_lshl_add_u64 v[224:225], s[34:35], 0, v[134:135]
	s_mov_b32 m0, s47
	s_nop 0
	global_load_lds_dwordx4 v134, s[34:35]
	s_waitcnt vmcnt(22)
	s_waitcnt lgkmcnt(0)
	s_barrier
	s_setprio 1
	v_mfma_f32_16x16x32_bf16 v[62:65], v[154:157], v[170:173], v[62:65]
	v_mfma_f32_16x16x32_bf16 v[58:61], v[162:165], v[170:173], v[58:61]
	v_mfma_f32_16x16x32_bf16 v[54:57], v[154:157], v[178:181], v[54:57]
	v_mfma_f32_16x16x32_bf16 v[46:49], v[162:165], v[178:181], v[46:49]
	v_mfma_f32_16x16x32_bf16 v[38:41], v[154:157], v[190:193], v[38:41]
	v_mfma_f32_16x16x32_bf16 v[30:33], v[162:165], v[190:193], v[30:33]
	v_mfma_f32_16x16x32_bf16 v[22:25], v[154:157], v[198:201], v[22:25]
	v_mfma_f32_16x16x32_bf16 v[14:17], v[162:165], v[198:201], v[14:17]
	v_mfma_f32_16x16x32_bf16 v[62:65], v[158:161], v[174:177], v[62:65]
	v_mfma_f32_16x16x32_bf16 v[58:61], v[166:169], v[174:177], v[58:61]
	v_mfma_f32_16x16x32_bf16 v[54:57], v[158:161], v[186:189], v[54:57]
	v_mfma_f32_16x16x32_bf16 v[46:49], v[166:169], v[186:189], v[46:49]
	v_mfma_f32_16x16x32_bf16 v[38:41], v[158:161], v[194:197], v[38:41]
	v_mfma_f32_16x16x32_bf16 v[30:33], v[166:169], v[194:197], v[30:33]
	v_mfma_f32_16x16x32_bf16 v[22:25], v[158:161], v[202:205], v[22:25]
	v_mfma_f32_16x16x32_bf16 v[14:17], v[166:169], v[202:205], v[14:17]
	v_mfma_f32_16x16x32_bf16 v[50:53], v[206:209], v[170:173], v[50:53]
	v_mfma_f32_16x16x32_bf16 v[42:45], v[214:217], v[170:173], v[42:45]
	v_mfma_f32_16x16x32_bf16 v[34:37], v[206:209], v[178:181], v[34:37]
	v_mfma_f32_16x16x32_bf16 v[26:29], v[214:217], v[178:181], v[26:29]
	v_mfma_f32_16x16x32_bf16 v[18:21], v[206:209], v[190:193], v[18:21]
	v_mfma_f32_16x16x32_bf16 v[10:13], v[214:217], v[190:193], v[10:13]
	v_mfma_f32_16x16x32_bf16 v[6:9], v[206:209], v[198:201], v[6:9]
	v_mfma_f32_16x16x32_bf16 v[2:5], v[214:217], v[198:201], v[2:5]
	v_mfma_f32_16x16x32_bf16 v[50:53], v[210:213], v[174:177], v[50:53]
	v_mfma_f32_16x16x32_bf16 v[42:45], v[218:221], v[174:177], v[42:45]
	v_mfma_f32_16x16x32_bf16 v[34:37], v[210:213], v[186:189], v[34:37]
	v_mfma_f32_16x16x32_bf16 v[26:29], v[218:221], v[186:189], v[26:29]
	v_mfma_f32_16x16x32_bf16 v[18:21], v[210:213], v[194:197], v[18:21]
	v_mfma_f32_16x16x32_bf16 v[10:13], v[218:221], v[194:197], v[10:13]
	v_mfma_f32_16x16x32_bf16 v[6:9], v[210:213], v[202:205], v[6:9]
	v_mfma_f32_16x16x32_bf16 v[2:5], v[218:221], v[202:205], v[2:5]
	s_setprio 0
	s_barrier
	s_add_u32 s28, s30, 0x20000
	s_addc_u32 s29, s31, 0
	s_add_i32 s82, s71, s45
	s_mov_b32 m0, s82
	s_nop 0
	global_load_lds_dwordx4 v132, s[28:29]
	s_add_i32 m0, s82, 0x2000
	s_nop 0
	global_load_lds_dwordx4 v136, s[28:29]
	s_add_i32 s82, 0, 0x18000
	v_add_u32_e32 v153, s82, v148
	ds_read_b128 v[154:157], v153
	ds_read_b128 v[158:161], v153 offset:1024
	ds_read_b128 v[162:165], v153 offset:2048
	ds_read_b128 v[166:169], v153 offset:3072
	s_add_u32 s28, s34, 0xf0000
	s_addc_u32 s29, s35, 0
	s_mov_b32 m0, s50
	ds_read_b128 v[170:173], v151 offset:32768
	ds_read_b128 v[174:177], v151 offset:33792
	ds_read_b128 v[178:181], v151 offset:34816
	ds_read_b128 v[186:189], v151 offset:35840
	ds_read_b128 v[190:193], v151 offset:36864
	ds_read_b128 v[194:197], v151 offset:37888
	ds_read_b128 v[198:201], v151 offset:38912
	ds_read_b128 v[202:205], v151 offset:39936
	v_add_u32_e32 v218, 0x1c000, v148
	ds_read_b128 v[206:209], v218
	ds_read_b128 v[210:213], v218 offset:1024
	ds_read_b128 v[214:217], v218 offset:2048
	ds_read_b128 v[218:221], v218 offset:3072
	global_load_lds_dwordx4 v130, s[28:29]
	s_mov_b32 m0, s51
	s_nop 0
	global_load_lds_dwordx4 v134, s[28:29]
	s_waitcnt vmcnt(8)
	s_waitcnt lgkmcnt(0)
	s_barrier
	s_setprio 1
	v_mfma_f32_16x16x32_bf16 v[126:129], v[154:157], v[170:173], v[126:129]
	v_mfma_f32_16x16x32_bf16 v[122:125], v[162:165], v[170:173], v[122:125]
	v_mfma_f32_16x16x32_bf16 v[114:117], v[154:157], v[178:181], v[114:117]
	v_mfma_f32_16x16x32_bf16 v[106:109], v[162:165], v[178:181], v[106:109]
	v_mfma_f32_16x16x32_bf16 v[98:101], v[154:157], v[190:193], v[98:101]
	v_mfma_f32_16x16x32_bf16 v[90:93], v[162:165], v[190:193], v[90:93]
	v_mfma_f32_16x16x32_bf16 v[82:85], v[154:157], v[198:201], v[82:85]
	v_mfma_f32_16x16x32_bf16 v[74:77], v[162:165], v[198:201], v[74:77]
	v_mfma_f32_16x16x32_bf16 v[126:129], v[158:161], v[174:177], v[126:129]
	v_mfma_f32_16x16x32_bf16 v[122:125], v[166:169], v[174:177], v[122:125]
	v_mfma_f32_16x16x32_bf16 v[114:117], v[158:161], v[186:189], v[114:117]
	v_mfma_f32_16x16x32_bf16 v[106:109], v[166:169], v[186:189], v[106:109]
	v_mfma_f32_16x16x32_bf16 v[98:101], v[158:161], v[194:197], v[98:101]
	v_mfma_f32_16x16x32_bf16 v[90:93], v[166:169], v[194:197], v[90:93]
	v_mfma_f32_16x16x32_bf16 v[82:85], v[158:161], v[202:205], v[82:85]
	v_mfma_f32_16x16x32_bf16 v[74:77], v[166:169], v[202:205], v[74:77]
	v_mfma_f32_16x16x32_bf16 v[118:121], v[206:209], v[170:173], v[118:121]
	v_mfma_f32_16x16x32_bf16 v[110:113], v[214:217], v[170:173], v[110:113]
	v_mfma_f32_16x16x32_bf16 v[102:105], v[206:209], v[178:181], v[102:105]
	v_mfma_f32_16x16x32_bf16 v[94:97], v[214:217], v[178:181], v[94:97]
	v_mfma_f32_16x16x32_bf16 v[86:89], v[206:209], v[190:193], v[86:89]
	v_mfma_f32_16x16x32_bf16 v[78:81], v[214:217], v[190:193], v[78:81]
	v_mfma_f32_16x16x32_bf16 v[70:73], v[206:209], v[198:201], v[70:73]
	v_mfma_f32_16x16x32_bf16 v[66:69], v[214:217], v[198:201], v[66:69]
	v_mfma_f32_16x16x32_bf16 v[118:121], v[210:213], v[174:177], v[118:121]
	v_mfma_f32_16x16x32_bf16 v[110:113], v[218:221], v[174:177], v[110:113]
	v_mfma_f32_16x16x32_bf16 v[102:105], v[210:213], v[186:189], v[102:105]
	v_mfma_f32_16x16x32_bf16 v[94:97], v[218:221], v[186:189], v[94:97]
	v_mfma_f32_16x16x32_bf16 v[86:89], v[210:213], v[194:197], v[86:89]
	v_mfma_f32_16x16x32_bf16 v[78:81], v[218:221], v[194:197], v[78:81]
	v_mfma_f32_16x16x32_bf16 v[70:73], v[210:213], v[202:205], v[70:73]
	v_mfma_f32_16x16x32_bf16 v[66:69], v[218:221], v[202:205], v[66:69]
	s_setprio 0
	s_barrier
	s_add_i32 s34, 0, 0x1c000
	s_add_i32 s28, s82, s45
	v_lshl_add_u64 v[146:147], v[146:147], 0, s[6:7]
	s_mov_b32 m0, s28
	global_load_lds_dwordx4 v[146:147], off
	v_lshl_add_u64 v[146:147], v[182:183], 0, s[6:7]
	s_add_i32 m0, s28, 0x2000
	s_nop 0
	global_load_lds_dwordx4 v[146:147], off
	s_mov_b32 m0, s53
	v_lshl_add_u64 v[146:147], v[222:223], 0, s[6:7]
	ds_read_b128 v[170:173], v151 offset:49152
	ds_read_b128 v[174:177], v151 offset:50176
	ds_read_b128 v[178:181], v151 offset:51200
	ds_read_b128 v[186:189], v151 offset:52224
	ds_read_b128 v[190:193], v151 offset:53248
	ds_read_b128 v[194:197], v151 offset:54272
	ds_read_b128 v[198:201], v151 offset:55296
	ds_read_b128 v[202:205], v151 offset:56320
	global_load_lds_dwordx4 v[146:147], off
	v_lshl_add_u64 v[146:147], v[224:225], 0, s[6:7]
	s_mov_b32 m0, s58
	s_nop 0
	global_load_lds_dwordx4 v[146:147], off
	s_add_u32 s28, s30, 0x20080
	s_addc_u32 s29, s31, 0
	s_add_i32 s30, s34, s45
	s_mov_b32 m0, s30
	s_nop 0
	global_load_lds_dwordx4 v132, s[28:29]
	s_add_i32 m0, s30, 0x2000
	s_nop 0
	global_load_lds_dwordx4 v136, s[28:29]
	s_waitcnt vmcnt(8)
	s_waitcnt lgkmcnt(0)
	s_barrier
	s_setprio 1
	v_mfma_f32_16x16x32_bf16 v[62:65], v[154:157], v[170:173], v[62:65]
	v_mfma_f32_16x16x32_bf16 v[58:61], v[162:165], v[170:173], v[58:61]
	v_mfma_f32_16x16x32_bf16 v[54:57], v[154:157], v[178:181], v[54:57]
	v_mfma_f32_16x16x32_bf16 v[46:49], v[162:165], v[178:181], v[46:49]
	v_mfma_f32_16x16x32_bf16 v[38:41], v[154:157], v[190:193], v[38:41]
	v_mfma_f32_16x16x32_bf16 v[30:33], v[162:165], v[190:193], v[30:33]
	v_mfma_f32_16x16x32_bf16 v[22:25], v[154:157], v[198:201], v[22:25]
	v_mfma_f32_16x16x32_bf16 v[14:17], v[162:165], v[198:201], v[14:17]
	v_mfma_f32_16x16x32_bf16 v[62:65], v[158:161], v[174:177], v[62:65]
	v_mfma_f32_16x16x32_bf16 v[58:61], v[166:169], v[174:177], v[58:61]
	v_mfma_f32_16x16x32_bf16 v[54:57], v[158:161], v[186:189], v[54:57]
	v_mfma_f32_16x16x32_bf16 v[46:49], v[166:169], v[186:189], v[46:49]
	v_mfma_f32_16x16x32_bf16 v[38:41], v[158:161], v[194:197], v[38:41]
	v_mfma_f32_16x16x32_bf16 v[30:33], v[166:169], v[194:197], v[30:33]
	v_mfma_f32_16x16x32_bf16 v[22:25], v[158:161], v[202:205], v[22:25]
	v_mfma_f32_16x16x32_bf16 v[14:17], v[166:169], v[202:205], v[14:17]
	v_mfma_f32_16x16x32_bf16 v[50:53], v[206:209], v[170:173], v[50:53]
	v_mfma_f32_16x16x32_bf16 v[42:45], v[214:217], v[170:173], v[42:45]
	v_mfma_f32_16x16x32_bf16 v[34:37], v[206:209], v[178:181], v[34:37]
	v_mfma_f32_16x16x32_bf16 v[26:29], v[214:217], v[178:181], v[26:29]
	v_mfma_f32_16x16x32_bf16 v[18:21], v[206:209], v[190:193], v[18:21]
	v_mfma_f32_16x16x32_bf16 v[10:13], v[214:217], v[190:193], v[10:13]
	v_mfma_f32_16x16x32_bf16 v[6:9], v[206:209], v[198:201], v[6:9]
	v_mfma_f32_16x16x32_bf16 v[2:5], v[214:217], v[198:201], v[2:5]
	v_mfma_f32_16x16x32_bf16 v[50:53], v[210:213], v[174:177], v[50:53]
	v_mfma_f32_16x16x32_bf16 v[42:45], v[218:221], v[174:177], v[42:45]
	v_mfma_f32_16x16x32_bf16 v[34:37], v[210:213], v[186:189], v[34:37]
	v_mfma_f32_16x16x32_bf16 v[26:29], v[218:221], v[186:189], v[26:29]
	v_mfma_f32_16x16x32_bf16 v[18:21], v[210:213], v[194:197], v[18:21]
	v_mfma_f32_16x16x32_bf16 v[10:13], v[218:221], v[194:197], v[10:13]
	v_mfma_f32_16x16x32_bf16 v[6:9], v[210:213], v[202:205], v[6:9]
	v_mfma_f32_16x16x32_bf16 v[2:5], v[218:221], v[202:205], v[2:5]
	s_setprio 0
	s_add_i32 s81, s81, 2
	s_add_u32 s79, s79, 0x100
	s_addc_u32 s80, s80, 0
	s_cmp_gt_u32 s81, 5
	s_mov_b64 s[28:29], s[4:5]
	s_barrier
	s_cbranch_scc1 .Lgemm_epi_1

.LBB0_802:
	s_ashr_i32 s15, s14, 31
	v_cmp_lt_i64_e32 vcc, s[18:19], v[190:191]
	s_lshl_b64 s[18:19], s[14:15], 20
	s_add_u32 s18, s23, s18
	s_addc_u32 s19, s26, s19
	s_and_b64 s[24:25], vcc, exec
	s_cselect_b32 s15, s19, s13
	s_cselect_b32 s45, s18, s12
	s_ashr_i32 s3, s2, 31
	s_lshl_b64 s[24:25], s[2:3], 20
	s_add_u32 s28, s73, s24
	s_addc_u32 s29, s36, s25
	s_and_b64 s[24:25], vcc, exec
	s_cselect_b32 s3, s29, s21
	s_cselect_b32 s52, s28, s20
	s_add_u32 s12, s12, 0x80080
	s_addc_u32 s13, s13, 0
	s_add_u32 s53, s20, 0x100
	v_mov_b32_e32 v0, 0
	s_addc_u32 s56, s21, 0
	s_mov_b32 s57, -2
	v_mov_b32_e32 v1, v0
	v_mov_b32_e32 v2, v0
	v_mov_b32_e32 v3, v0
	v_mov_b32_e32 v4, v0
	v_mov_b32_e32 v5, v0
	v_mov_b32_e32 v6, v0
	v_mov_b32_e32 v7, v0
	v_mov_b32_e32 v16, v0
	v_mov_b32_e32 v17, v0
	v_mov_b32_e32 v18, v0
	v_mov_b32_e32 v19, v0
	v_mov_b32_e32 v20, v0
	v_mov_b32_e32 v21, v0
	v_mov_b32_e32 v22, v0
	v_mov_b32_e32 v23, v0
	v_mov_b32_e32 v32, v0
	v_mov_b32_e32 v33, v0
	v_mov_b32_e32 v34, v0
	v_mov_b32_e32 v35, v0
	v_mov_b32_e32 v36, v0
	v_mov_b32_e32 v37, v0
	v_mov_b32_e32 v38, v0
	v_mov_b32_e32 v39, v0
	v_mov_b32_e32 v48, v0
	v_mov_b32_e32 v49, v0
	v_mov_b32_e32 v50, v0
	v_mov_b32_e32 v51, v0
	v_mov_b32_e32 v52, v0
	v_mov_b32_e32 v53, v0
	v_mov_b32_e32 v54, v0
	v_mov_b32_e32 v55, v0
	v_mov_b32_e32 v8, v0
	v_mov_b32_e32 v9, v0
	v_mov_b32_e32 v10, v0
	v_mov_b32_e32 v11, v0
	v_mov_b32_e32 v12, v0
	v_mov_b32_e32 v13, v0
	v_mov_b32_e32 v14, v0
	v_mov_b32_e32 v15, v0
	v_mov_b32_e32 v24, v0
	v_mov_b32_e32 v25, v0
	v_mov_b32_e32 v26, v0
	v_mov_b32_e32 v27, v0
	v_mov_b32_e32 v28, v0
	v_mov_b32_e32 v29, v0
	v_mov_b32_e32 v30, v0
	v_mov_b32_e32 v31, v0
	v_mov_b32_e32 v40, v0
	v_mov_b32_e32 v41, v0
	v_mov_b32_e32 v42, v0
	v_mov_b32_e32 v43, v0
	v_mov_b32_e32 v44, v0
	v_mov_b32_e32 v45, v0
	v_mov_b32_e32 v46, v0
	v_mov_b32_e32 v47, v0
	v_mov_b32_e32 v56, v0
	v_mov_b32_e32 v57, v0
	v_mov_b32_e32 v58, v0
	v_mov_b32_e32 v59, v0
	v_mov_b32_e32 v60, v0
	v_mov_b32_e32 v61, v0
	v_mov_b32_e32 v62, v0
	v_mov_b32_e32 v63, v0
	v_mov_b32_e32 v64, v0
	v_mov_b32_e32 v65, v0
	v_mov_b32_e32 v66, v0
	v_mov_b32_e32 v67, v0
	v_mov_b32_e32 v68, v0
	v_mov_b32_e32 v69, v0
	v_mov_b32_e32 v70, v0
	v_mov_b32_e32 v71, v0
	v_mov_b32_e32 v80, v0
	v_mov_b32_e32 v81, v0
	v_mov_b32_e32 v82, v0
	v_mov_b32_e32 v83, v0
	v_mov_b32_e32 v84, v0
	v_mov_b32_e32 v85, v0
	v_mov_b32_e32 v86, v0
	v_mov_b32_e32 v87, v0
	v_mov_b32_e32 v96, v0
	v_mov_b32_e32 v97, v0
	v_mov_b32_e32 v98, v0
	v_mov_b32_e32 v99, v0
	v_mov_b32_e32 v100, v0
	v_mov_b32_e32 v101, v0
	v_mov_b32_e32 v102, v0
	v_mov_b32_e32 v103, v0
	v_mov_b32_e32 v112, v0
	v_mov_b32_e32 v113, v0
	v_mov_b32_e32 v114, v0
	v_mov_b32_e32 v115, v0
	v_mov_b32_e32 v116, v0
	v_mov_b32_e32 v117, v0
	v_mov_b32_e32 v118, v0
	v_mov_b32_e32 v119, v0
	v_mov_b32_e32 v72, v0
	v_mov_b32_e32 v73, v0
	v_mov_b32_e32 v74, v0
	v_mov_b32_e32 v75, v0
	v_mov_b32_e32 v76, v0
	v_mov_b32_e32 v77, v0
	v_mov_b32_e32 v78, v0
	v_mov_b32_e32 v79, v0
	v_mov_b32_e32 v88, v0
	v_mov_b32_e32 v89, v0
	v_mov_b32_e32 v90, v0
	v_mov_b32_e32 v91, v0
	v_mov_b32_e32 v92, v0
	v_mov_b32_e32 v93, v0
	v_mov_b32_e32 v94, v0
	v_mov_b32_e32 v95, v0
	v_mov_b32_e32 v104, v0
	v_mov_b32_e32 v105, v0
	v_mov_b32_e32 v106, v0
	v_mov_b32_e32 v107, v0
	v_mov_b32_e32 v108, v0
	v_mov_b32_e32 v109, v0
	v_mov_b32_e32 v110, v0
	v_mov_b32_e32 v111, v0
	v_mov_b32_e32 v120, v0
	v_mov_b32_e32 v121, v0
	v_mov_b32_e32 v122, v0
	v_mov_b32_e32 v123, v0
	v_mov_b32_e32 v124, v0
	v_mov_b32_e32 v125, v0
	v_mov_b32_e32 v126, v0
	v_mov_b32_e32 v127, v0
	s_cmp_eq_u32 s98, 0
	s_cbranch_scc1 .LBB0_803
	s_add_u32 s4, s12, 0xfff80080
	s_addc_u32 s20, s13, -1
	s_add_i32 s58, 0, 0x10000
	v_add_u32_e32 v140, s58, v161
	ds_read_b128 v[128:131], v140
	ds_read_b128 v[132:135], v140 offset:1024
	ds_read_b128 v[136:139], v140 offset:2048
	ds_read_b128 v[140:143], v140 offset:3072
	s_cmp_eq_u32 s57, 28
	s_cselect_b32 s25, s15, s20
	s_cselect_b32 s24, s45, s4
	s_cselect_b32 s21, s3, s56
	s_cselect_b32 s20, s52, s53
	v_lshl_add_u64 v[158:159], s[12:13], 0, v[150:151]
	s_add_i32 m0, s16, 0xc000
	ds_read_b128 v[154:157], v163
	ds_read_b128 v[164:167], v163 offset:1024
	ds_read_b128 v[168:171], v163 offset:2048
	ds_read_b128 v[172:175], v163 offset:3072
	ds_read_b128 v[176:179], v163 offset:4096
	ds_read_b128 v[180:183], v163 offset:5120
	ds_read_b128 v[196:199], v163 offset:6144
	ds_read_b128 v[200:203], v163 offset:7168
	v_add_u32_e32 v216, 0x14000, v161
	ds_read_b128 v[204:207], v216
	ds_read_b128 v[208:211], v216 offset:1024
	ds_read_b128 v[212:215], v216 offset:2048
	ds_read_b128 v[216:219], v216 offset:3072
	global_load_lds_dwordx4 v150, s[12:13]
	v_lshl_add_u64 v[158:159], s[12:13], 0, v[152:153]
	s_add_i32 m0, s16, 0xe000
	s_nop 0
	global_load_lds_dwordx4 v152, s[12:13]
	s_waitcnt vmcnt(24)
	s_waitcnt lgkmcnt(0)
	s_barrier
	s_setprio 1
	v_mfma_f32_16x16x32_bf16 v[124:127], v[128:131], v[154:157], v[124:127]
	v_mfma_f32_16x16x32_bf16 v[120:123], v[136:139], v[154:157], v[120:123]
	v_mfma_f32_16x16x32_bf16 v[108:111], v[128:131], v[168:171], v[108:111]
	v_mfma_f32_16x16x32_bf16 v[104:107], v[136:139], v[168:171], v[104:107]
	v_mfma_f32_16x16x32_bf16 v[92:95], v[128:131], v[176:179], v[92:95]
	v_mfma_f32_16x16x32_bf16 v[88:91], v[136:139], v[176:179], v[88:91]
	v_mfma_f32_16x16x32_bf16 v[76:79], v[128:131], v[196:199], v[76:79]
	v_mfma_f32_16x16x32_bf16 v[72:75], v[136:139], v[196:199], v[72:75]
	v_mfma_f32_16x16x32_bf16 v[124:127], v[132:135], v[164:167], v[124:127]
	v_mfma_f32_16x16x32_bf16 v[120:123], v[140:143], v[164:167], v[120:123]
	v_mfma_f32_16x16x32_bf16 v[108:111], v[132:135], v[172:175], v[108:111]
	v_mfma_f32_16x16x32_bf16 v[104:107], v[140:143], v[172:175], v[104:107]
	v_mfma_f32_16x16x32_bf16 v[92:95], v[132:135], v[180:183], v[92:95]
	v_mfma_f32_16x16x32_bf16 v[88:91], v[140:143], v[180:183], v[88:91]
	v_mfma_f32_16x16x32_bf16 v[76:79], v[132:135], v[200:203], v[76:79]
	v_mfma_f32_16x16x32_bf16 v[72:75], v[140:143], v[200:203], v[72:75]
	v_mfma_f32_16x16x32_bf16 v[116:119], v[204:207], v[154:157], v[116:119]
	v_mfma_f32_16x16x32_bf16 v[112:115], v[212:215], v[154:157], v[112:115]
	v_mfma_f32_16x16x32_bf16 v[100:103], v[204:207], v[168:171], v[100:103]
	v_mfma_f32_16x16x32_bf16 v[96:99], v[212:215], v[168:171], v[96:99]
	v_mfma_f32_16x16x32_bf16 v[84:87], v[204:207], v[176:179], v[84:87]
	v_mfma_f32_16x16x32_bf16 v[80:83], v[212:215], v[176:179], v[80:83]
	v_mfma_f32_16x16x32_bf16 v[68:71], v[204:207], v[196:199], v[68:71]
	v_mfma_f32_16x16x32_bf16 v[64:67], v[212:215], v[196:199], v[64:67]
	v_mfma_f32_16x16x32_bf16 v[116:119], v[208:211], v[164:167], v[116:119]
	v_mfma_f32_16x16x32_bf16 v[112:115], v[216:219], v[164:167], v[112:115]
	v_mfma_f32_16x16x32_bf16 v[100:103], v[208:211], v[172:175], v[100:103]
	v_mfma_f32_16x16x32_bf16 v[96:99], v[216:219], v[172:175], v[96:99]
	v_mfma_f32_16x16x32_bf16 v[84:87], v[208:211], v[180:183], v[84:87]
	v_mfma_f32_16x16x32_bf16 v[80:83], v[216:219], v[180:183], v[80:83]
	v_mfma_f32_16x16x32_bf16 v[68:71], v[208:211], v[200:203], v[68:71]
	v_mfma_f32_16x16x32_bf16 v[64:67], v[216:219], v[200:203], v[64:67]
	s_setprio 0
	s_barrier
	s_add_i32 s4, 0, 0x14000
	s_add_i32 s58, s58, s27
	v_lshl_add_u64 v[158:159], s[20:21], 0, v[186:187]
	s_mov_b32 m0, s58
	v_lshl_add_u64 v[220:221], s[20:21], 0, v[144:145]
	global_load_lds_dwordx4 v186, s[20:21]
	s_add_i32 m0, s58, 0x2000
	s_nop 0
	global_load_lds_dwordx4 v144, s[20:21]
	s_mov_b32 m0, s16
	v_lshl_add_u64 v[222:223], s[24:25], 0, v[148:149]
	ds_read_b128 v[154:157], v163 offset:16384
	ds_read_b128 v[164:167], v163 offset:17408
	ds_read_b128 v[168:171], v163 offset:18432
	ds_read_b128 v[172:175], v163 offset:19456
	ds_read_b128 v[176:179], v163 offset:20480
	ds_read_b128 v[180:183], v163 offset:21504
	ds_read_b128 v[196:199], v163 offset:22528
	ds_read_b128 v[200:203], v163 offset:23552
	global_load_lds_dwordx4 v148, s[24:25]
	v_lshl_add_u64 v[224:225], s[24:25], 0, v[146:147]
	s_mov_b32 m0, s17
	s_nop 0
	global_load_lds_dwordx4 v146, s[24:25]
	s_waitcnt vmcnt(22)
	s_waitcnt lgkmcnt(0)
	s_barrier
	s_setprio 1
	v_mfma_f32_16x16x32_bf16 v[60:63], v[128:131], v[154:157], v[60:63]
	v_mfma_f32_16x16x32_bf16 v[56:59], v[136:139], v[154:157], v[56:59]
	v_mfma_f32_16x16x32_bf16 v[44:47], v[128:131], v[168:171], v[44:47]
	v_mfma_f32_16x16x32_bf16 v[40:43], v[136:139], v[168:171], v[40:43]
	v_mfma_f32_16x16x32_bf16 v[28:31], v[128:131], v[176:179], v[28:31]
	v_mfma_f32_16x16x32_bf16 v[24:27], v[136:139], v[176:179], v[24:27]
	v_mfma_f32_16x16x32_bf16 v[12:15], v[128:131], v[196:199], v[12:15]
	v_mfma_f32_16x16x32_bf16 v[8:11], v[136:139], v[196:199], v[8:11]
	v_mfma_f32_16x16x32_bf16 v[60:63], v[132:135], v[164:167], v[60:63]
	v_mfma_f32_16x16x32_bf16 v[56:59], v[140:143], v[164:167], v[56:59]
	v_mfma_f32_16x16x32_bf16 v[44:47], v[132:135], v[172:175], v[44:47]
	v_mfma_f32_16x16x32_bf16 v[40:43], v[140:143], v[172:175], v[40:43]
	v_mfma_f32_16x16x32_bf16 v[28:31], v[132:135], v[180:183], v[28:31]
	v_mfma_f32_16x16x32_bf16 v[24:27], v[140:143], v[180:183], v[24:27]
	v_mfma_f32_16x16x32_bf16 v[12:15], v[132:135], v[200:203], v[12:15]
	v_mfma_f32_16x16x32_bf16 v[8:11], v[140:143], v[200:203], v[8:11]
	v_mfma_f32_16x16x32_bf16 v[52:55], v[204:207], v[154:157], v[52:55]
	v_mfma_f32_16x16x32_bf16 v[48:51], v[212:215], v[154:157], v[48:51]
	v_mfma_f32_16x16x32_bf16 v[36:39], v[204:207], v[168:171], v[36:39]
	v_mfma_f32_16x16x32_bf16 v[32:35], v[212:215], v[168:171], v[32:35]
	v_mfma_f32_16x16x32_bf16 v[20:23], v[204:207], v[176:179], v[20:23]
	v_mfma_f32_16x16x32_bf16 v[16:19], v[212:215], v[176:179], v[16:19]
	v_mfma_f32_16x16x32_bf16 v[4:7], v[204:207], v[196:199], v[4:7]
	v_mfma_f32_16x16x32_bf16 v[0:3], v[212:215], v[196:199], v[0:3]
	v_mfma_f32_16x16x32_bf16 v[52:55], v[208:211], v[164:167], v[52:55]
	v_mfma_f32_16x16x32_bf16 v[48:51], v[216:219], v[164:167], v[48:51]
	v_mfma_f32_16x16x32_bf16 v[36:39], v[208:211], v[172:175], v[36:39]
	v_mfma_f32_16x16x32_bf16 v[32:35], v[216:219], v[172:175], v[32:35]
	v_mfma_f32_16x16x32_bf16 v[20:23], v[208:211], v[180:183], v[20:23]
	v_mfma_f32_16x16x32_bf16 v[16:19], v[216:219], v[180:183], v[16:19]
	v_mfma_f32_16x16x32_bf16 v[4:7], v[208:211], v[200:203], v[4:7]
	v_mfma_f32_16x16x32_bf16 v[0:3], v[216:219], v[200:203], v[0:3]
	s_setprio 0
	s_barrier
	s_add_u32 s58, s20, 0x80000
	s_addc_u32 s59, s21, 0
	s_add_i32 s4, s4, s27
	s_mov_b32 m0, s4
	s_nop 0
	global_load_lds_dwordx4 v186, s[58:59]
	s_add_i32 m0, s4, 0x2000
	s_nop 0
	global_load_lds_dwordx4 v144, s[58:59]
	s_add_i32 s4, 0, 0x18000
	v_add_u32_e32 v140, s4, v161
	ds_read_b128 v[128:131], v140
	ds_read_b128 v[132:135], v140 offset:1024
	ds_read_b128 v[136:139], v140 offset:2048
	ds_read_b128 v[140:143], v140 offset:3072
	s_add_u32 s24, s24, 0x80000
	s_addc_u32 s25, s25, 0
	s_mov_b32 m0, s30
	ds_read_b128 v[154:157], v163 offset:32768
	ds_read_b128 v[164:167], v163 offset:33792
	ds_read_b128 v[168:171], v163 offset:34816
	ds_read_b128 v[172:175], v163 offset:35840
	ds_read_b128 v[176:179], v163 offset:36864
	ds_read_b128 v[180:183], v163 offset:37888
	ds_read_b128 v[196:199], v163 offset:38912
	ds_read_b128 v[200:203], v163 offset:39936
	v_add_u32_e32 v216, 0x1c000, v161
	ds_read_b128 v[204:207], v216
	ds_read_b128 v[208:211], v216 offset:1024
	ds_read_b128 v[212:215], v216 offset:2048
	ds_read_b128 v[216:219], v216 offset:3072
	global_load_lds_dwordx4 v148, s[24:25]
	s_mov_b32 m0, s31
	s_nop 0
	global_load_lds_dwordx4 v146, s[24:25]
	s_waitcnt vmcnt(8)
	s_waitcnt lgkmcnt(0)
	s_barrier
	s_setprio 1
	v_mfma_f32_16x16x32_bf16 v[124:127], v[128:131], v[154:157], v[124:127]
	v_mfma_f32_16x16x32_bf16 v[120:123], v[136:139], v[154:157], v[120:123]
	v_mfma_f32_16x16x32_bf16 v[108:111], v[128:131], v[168:171], v[108:111]
	v_mfma_f32_16x16x32_bf16 v[104:107], v[136:139], v[168:171], v[104:107]
	v_mfma_f32_16x16x32_bf16 v[92:95], v[128:131], v[176:179], v[92:95]
	v_mfma_f32_16x16x32_bf16 v[88:91], v[136:139], v[176:179], v[88:91]
	v_mfma_f32_16x16x32_bf16 v[76:79], v[128:131], v[196:199], v[76:79]
	v_mfma_f32_16x16x32_bf16 v[72:75], v[136:139], v[196:199], v[72:75]
	v_mfma_f32_16x16x32_bf16 v[124:127], v[132:135], v[164:167], v[124:127]
	v_mfma_f32_16x16x32_bf16 v[120:123], v[140:143], v[164:167], v[120:123]
	v_mfma_f32_16x16x32_bf16 v[108:111], v[132:135], v[172:175], v[108:111]
	v_mfma_f32_16x16x32_bf16 v[104:107], v[140:143], v[172:175], v[104:107]
	v_mfma_f32_16x16x32_bf16 v[92:95], v[132:135], v[180:183], v[92:95]
	v_mfma_f32_16x16x32_bf16 v[88:91], v[140:143], v[180:183], v[88:91]
	v_mfma_f32_16x16x32_bf16 v[76:79], v[132:135], v[200:203], v[76:79]
	v_mfma_f32_16x16x32_bf16 v[72:75], v[140:143], v[200:203], v[72:75]
	v_mfma_f32_16x16x32_bf16 v[116:119], v[204:207], v[154:157], v[116:119]
	v_mfma_f32_16x16x32_bf16 v[112:115], v[212:215], v[154:157], v[112:115]
	v_mfma_f32_16x16x32_bf16 v[100:103], v[204:207], v[168:171], v[100:103]
	v_mfma_f32_16x16x32_bf16 v[96:99], v[212:215], v[168:171], v[96:99]
	v_mfma_f32_16x16x32_bf16 v[84:87], v[204:207], v[176:179], v[84:87]
	v_mfma_f32_16x16x32_bf16 v[80:83], v[212:215], v[176:179], v[80:83]
	v_mfma_f32_16x16x32_bf16 v[68:71], v[204:207], v[196:199], v[68:71]
	v_mfma_f32_16x16x32_bf16 v[64:67], v[212:215], v[196:199], v[64:67]
	v_mfma_f32_16x16x32_bf16 v[116:119], v[208:211], v[164:167], v[116:119]
	v_mfma_f32_16x16x32_bf16 v[112:115], v[216:219], v[164:167], v[112:115]
	v_mfma_f32_16x16x32_bf16 v[100:103], v[208:211], v[172:175], v[100:103]
	v_mfma_f32_16x16x32_bf16 v[96:99], v[216:219], v[172:175], v[96:99]
	v_mfma_f32_16x16x32_bf16 v[84:87], v[208:211], v[180:183], v[84:87]
	v_mfma_f32_16x16x32_bf16 v[80:83], v[216:219], v[180:183], v[80:83]
	v_mfma_f32_16x16x32_bf16 v[68:71], v[208:211], v[200:203], v[68:71]
	v_mfma_f32_16x16x32_bf16 v[64:67], v[216:219], v[200:203], v[64:67]
	s_setprio 0
	s_barrier
	s_add_i32 s24, 0, 0x1c000
	s_add_i32 s4, s4, s27
	v_lshl_add_u64 v[158:159], v[158:159], 0, s[0:1]
	s_mov_b32 m0, s4
	global_load_lds_dwordx4 v[158:159], off
	v_lshl_add_u64 v[158:159], v[220:221], 0, s[0:1]
	s_add_i32 m0, s4, 0x2000
	s_nop 0
	global_load_lds_dwordx4 v[158:159], off
	s_mov_b32 m0, s38
	v_lshl_add_u64 v[158:159], v[222:223], 0, s[0:1]
	ds_read_b128 v[154:157], v163 offset:49152
	ds_read_b128 v[164:167], v163 offset:50176
	ds_read_b128 v[168:171], v163 offset:51200
	ds_read_b128 v[172:175], v163 offset:52224
	ds_read_b128 v[176:179], v163 offset:53248
	ds_read_b128 v[180:183], v163 offset:54272
	ds_read_b128 v[196:199], v163 offset:55296
	ds_read_b128 v[200:203], v163 offset:56320
	global_load_lds_dwordx4 v[158:159], off
	v_lshl_add_u64 v[158:159], v[224:225], 0, s[0:1]
	s_mov_b32 m0, s39
	s_nop 0
	global_load_lds_dwordx4 v[158:159], off
	s_add_u32 s20, s20, 0x80080
	s_addc_u32 s21, s21, 0
	s_add_i32 s4, s24, s27
	s_mov_b32 m0, s4
	s_nop 0
	global_load_lds_dwordx4 v186, s[20:21]
	s_add_i32 m0, s4, 0x2000
	s_nop 0
	global_load_lds_dwordx4 v144, s[20:21]
	s_waitcnt vmcnt(8)
	s_waitcnt lgkmcnt(0)
	s_barrier
	s_setprio 1
	v_mfma_f32_16x16x32_bf16 v[60:63], v[128:131], v[154:157], v[60:63]
	v_mfma_f32_16x16x32_bf16 v[56:59], v[136:139], v[154:157], v[56:59]
	v_mfma_f32_16x16x32_bf16 v[44:47], v[128:131], v[168:171], v[44:47]
	v_mfma_f32_16x16x32_bf16 v[40:43], v[136:139], v[168:171], v[40:43]
	v_mfma_f32_16x16x32_bf16 v[28:31], v[128:131], v[176:179], v[28:31]
	v_mfma_f32_16x16x32_bf16 v[24:27], v[136:139], v[176:179], v[24:27]
	v_mfma_f32_16x16x32_bf16 v[12:15], v[128:131], v[196:199], v[12:15]
	v_mfma_f32_16x16x32_bf16 v[8:11], v[136:139], v[196:199], v[8:11]
	v_mfma_f32_16x16x32_bf16 v[60:63], v[132:135], v[164:167], v[60:63]
	v_mfma_f32_16x16x32_bf16 v[56:59], v[140:143], v[164:167], v[56:59]
	v_mfma_f32_16x16x32_bf16 v[44:47], v[132:135], v[172:175], v[44:47]
	v_mfma_f32_16x16x32_bf16 v[40:43], v[140:143], v[172:175], v[40:43]
	v_mfma_f32_16x16x32_bf16 v[28:31], v[132:135], v[180:183], v[28:31]
	v_mfma_f32_16x16x32_bf16 v[24:27], v[140:143], v[180:183], v[24:27]
	v_mfma_f32_16x16x32_bf16 v[12:15], v[132:135], v[200:203], v[12:15]
	v_mfma_f32_16x16x32_bf16 v[8:11], v[140:143], v[200:203], v[8:11]
	v_mfma_f32_16x16x32_bf16 v[52:55], v[204:207], v[154:157], v[52:55]
	v_mfma_f32_16x16x32_bf16 v[48:51], v[212:215], v[154:157], v[48:51]
	v_mfma_f32_16x16x32_bf16 v[36:39], v[204:207], v[168:171], v[36:39]
	v_mfma_f32_16x16x32_bf16 v[32:35], v[212:215], v[168:171], v[32:35]
	v_mfma_f32_16x16x32_bf16 v[20:23], v[204:207], v[176:179], v[20:23]
	v_mfma_f32_16x16x32_bf16 v[16:19], v[212:215], v[176:179], v[16:19]
	v_mfma_f32_16x16x32_bf16 v[4:7], v[204:207], v[196:199], v[4:7]
	v_mfma_f32_16x16x32_bf16 v[0:3], v[212:215], v[196:199], v[0:3]
	v_mfma_f32_16x16x32_bf16 v[52:55], v[208:211], v[164:167], v[52:55]
	v_mfma_f32_16x16x32_bf16 v[48:51], v[216:219], v[164:167], v[48:51]
	v_mfma_f32_16x16x32_bf16 v[36:39], v[208:211], v[172:175], v[36:39]
	v_mfma_f32_16x16x32_bf16 v[32:35], v[216:219], v[172:175], v[32:35]
	v_mfma_f32_16x16x32_bf16 v[20:23], v[208:211], v[180:183], v[20:23]
	v_mfma_f32_16x16x32_bf16 v[16:19], v[216:219], v[180:183], v[16:19]
	v_mfma_f32_16x16x32_bf16 v[4:7], v[208:211], v[200:203], v[4:7]
	v_mfma_f32_16x16x32_bf16 v[0:3], v[216:219], v[200:203], v[0:3]
	s_setprio 0
	s_add_i32 s57, s57, 2
	s_add_u32 s12, s12, 0x100
	s_addc_u32 s13, s13, 0
	s_add_u32 s53, s53, 0x100
	s_addc_u32 s56, s56, 0
	s_cmp_gt_u32 s57, 29
	s_barrier
	s_cbranch_scc1 .Lgemm_epi_2
